# P11 final-norm loop: second row's loads and all gain loads of an iteration issued up front (counted waits); padded a 128-bit store-data WAR wait state in the P10 epilogue and a v_cmp->v_cndmask wait s
# baseline (speedup 1.0000x reference)
; #define GAS __attribute__((address_space(1)))
; DI unsigned pk2(float a, float b) { f32x2 v = {a, b}; bf16x2_t r = __builtin_convertvector(v, bf16x2_t); return __builtin_bit_cast(unsigned, r); }
; DI float bflo(unsigned u) { return __uint_as_float(u << 16); }
; DI float bfhi(unsigned u) { return __uint_as_float(u & 0xffff0000u); }
; DI void store_bf16_row32(bf16_t* rowp, const float (&v)[16], int hh) {
; #pragma unroll
;     for (int p = 0; p < 2; ++p) {
;         unsigned ax = pk2(v[8 * p + 0], v[8 * p + 1]), ay = pk2(v[8 * p + 2], v[8 * p + 3]);
;         unsigned bx = pk2(v[8 * p + 4], v[8 * p + 5]), by = pk2(v[8 * p + 6], v[8 * p + 7]);
;         const auto rx = __builtin_amdgcn_permlane32_swap(ax, bx, false, false);
;         const auto ry = __builtin_amdgcn_permlane32_swap(ay, by, false, false);
;         u32x4 w; w.x = rx[0]; w.y = ry[0]; w.z = rx[1]; w.w = ry[1];
;         *(GAS u32x4*)(rowp + 16 * p + 8 * hh) = w;
;     }
; }
;     DI void operator()(int fbase, int tbase, const f32x16& acc, int r, int hh) const {
;         const int t = tbase + r;
;         const bf16_t* res = xb + (size_t)t * D; const float* gate = mods_l + (t >> 13) * 3072 + 2048;
;         float o[16];
; #pragma unroll
;         for (int g = 0; g < 4; ++g) {
;             const int f = fbase + 8 * g + 4 * hh;
;             const u32x2 rb = *(const GAS u32x2*)(res + f); const f32x4 gg = *(const GAS f32x4*)(gate + f);
;             o[4 * g] = bflo(rb.x) + gg.x * acc[4 * g]; o[4 * g + 1] = bfhi(rb.x) + gg.y * acc[4 * g + 1]; o[4 * g + 2] = bflo(rb.y) + gg.z * acc[4 * g + 2]; o[4 * g + 3] = bfhi(rb.y) + gg.w * acc[4 * g + 3];
;         }
;         store_bf16_row32(x2b + (size_t)t * D + fbase, o, hh);
;     }
.LBB0_1173:
	s_ashr_i32 s55, s54, 31
	s_lshr_b32 s55, s55, 30
	s_add_i32 s55, s54, s55
	s_lshr_b32 s56, s55, 2
	s_lshl_b32 s56, s56, s27
	s_and_b32 s55, s55, 0xfffffc
	s_add_i32 s56, s56, s33
	s_sub_i32 s54, s54, s55
	v_lshl_add_u32 v149, s56, 8, v188
	v_lshl_or_b32 v154, s54, 8, v187
	v_or_b32_e32 v166, v149, v183
	v_or_b32_e32 v156, v154, v146
	v_ashrrev_i32_e32 v167, 31, v166
	v_ashrrev_i32_e32 v157, 31, v156
	v_lshlrev_b64 v[160:161], 11, v[166:167]
	v_ashrrev_i32_e32 v149, 13, v149
	v_lshl_add_u64 v[162:163], s[8:9], 0, v[160:161]
	v_lshlrev_b64 v[176:177], 1, v[156:157]
	v_mul_i32_i24_e32 v164, 0xc00, v149
	v_lshl_add_u64 v[158:159], v[162:163], 0, v[176:177]
	v_ashrrev_i32_e32 v165, 31, v164
	global_load_dwordx2 v[200:201], v[158:159], off
	global_load_dwordx2 v[212:213], v[158:159], off offset:16
	global_load_dwordx2 v[214:215], v[158:159], off offset:32
	global_load_dwordx2 v[216:217], v[158:159], off offset:48
	v_or_b32_e32 v170, 8, v156
	v_lshl_add_u64 v[158:159], v[164:165], 2, s[10:11]
	v_ashrrev_i32_e32 v171, 31, v170
	v_or_b32_e32 v172, 16, v156
	v_or_b32_e32 v174, 24, v156
	v_lshl_add_u64 v[158:159], v[158:159], 0, s[40:41]
	v_ashrrev_i32_e32 v173, 31, v172
	v_ashrrev_i32_e32 v175, 31, v174
	v_lshl_add_u64 v[168:169], v[156:157], 2, v[158:159]
	v_lshl_add_u64 v[170:171], v[170:171], 2, v[158:159]
	global_load_dwordx4 v[192:195], v[168:169], off
	global_load_dwordx4 v[196:199], v[170:171], off
	v_lshl_add_u64 v[172:173], v[172:173], 2, v[158:159]
	v_lshl_add_u64 v[174:175], v[174:175], 2, v[158:159]
	global_load_dwordx4 v[204:207], v[172:173], off
	global_load_dwordx4 v[208:211], v[174:175], off
	v_ashrrev_i32_e32 v155, 31, v154
	v_or_b32_e32 v156, 32, v166
	v_lshlrev_b64 v[164:165], 1, v[154:155]
	v_ashrrev_i32_e32 v157, 31, v156
	v_lshl_add_u64 v[160:161], s[12:13], 0, v[160:161]
	v_lshlrev_b64 v[218:219], 11, v[156:157]
	v_lshl_add_u64 v[156:157], v[160:161], 0, v[164:165]
	v_lshl_add_u64 v[160:161], s[8:9], 0, v[218:219]
	v_lshl_add_u64 v[156:157], v[156:157], 0, v[128:129]
	v_lshl_add_u64 v[220:221], v[160:161], 0, v[176:177]
	s_andn2_b64 vcc, exec, s[42:43]
	s_waitcnt vmcnt(0)
	global_load_dwordx2 v[238:239], v[220:221], off
	global_load_dwordx2 v[240:241], v[220:221], off offset:16
	global_load_dwordx2 v[242:243], v[220:221], off offset:32
	global_load_dwordx2 v[244:245], v[220:221], off offset:48
	v_lshlrev_b32_e32 v222, 16, v200
	v_and_b32_e32 v223, 0xffff0000, v200
	v_lshlrev_b32_e32 v200, 16, v201
	v_and_b32_e32 v201, 0xffff0000, v201
	v_lshlrev_b32_e32 v224, 16, v212
	v_and_b32_e32 v225, 0xffff0000, v212
	v_lshlrev_b32_e32 v212, 16, v213
	v_and_b32_e32 v213, 0xffff0000, v213
	v_lshlrev_b32_e32 v226, 16, v214
	v_and_b32_e32 v227, 0xffff0000, v214
	v_lshlrev_b32_e32 v214, 16, v215
	v_and_b32_e32 v215, 0xffff0000, v215
	v_lshlrev_b32_e32 v228, 16, v216
	v_and_b32_e32 v229, 0xffff0000, v216
	v_lshlrev_b32_e32 v216, 16, v217
	v_and_b32_e32 v217, 0xffff0000, v217
	v_pk_fma_f32 v[112:113], v[112:113], v[192:193], v[222:223]
	v_pk_fma_f32 v[114:115], v[114:115], v[194:195], v[200:201]
	v_pk_fma_f32 v[116:117], v[116:117], v[196:197], v[224:225]
	v_pk_fma_f32 v[118:119], v[118:119], v[198:199], v[212:213]
	v_pk_fma_f32 v[120:121], v[120:121], v[204:205], v[226:227]
	v_pk_fma_f32 v[122:123], v[122:123], v[206:207], v[214:215]
	v_pk_fma_f32 v[124:125], v[124:125], v[208:209], v[228:229]
	v_pk_fma_f32 v[126:127], v[126:127], v[210:211], v[216:217]
	v_cvt_pk_bf16_f32 v112, v112, v113
	v_cvt_pk_bf16_f32 v113, v114, v115
	v_cvt_pk_bf16_f32 v114, v116, v117
	v_cvt_pk_bf16_f32 v115, v118, v119
	v_cvt_pk_bf16_f32 v116, v120, v121
	v_cvt_pk_bf16_f32 v117, v122, v123
	v_cvt_pk_bf16_f32 v118, v124, v125
	v_cvt_pk_bf16_f32 v119, v126, v127
	v_permlane32_swap_b32_e32 v112, v114
	v_permlane32_swap_b32_e32 v113, v115
	v_permlane32_swap_b32_e32 v116, v118
	v_permlane32_swap_b32_e32 v117, v119
	global_store_dwordx4 v[156:157], v[112:115], off
	global_store_dwordx4 v[156:157], v[116:119], off offset:32
	s_nop 0
	global_load_dwordx4 v[116:119], v[168:169], off
	global_load_dwordx4 v[120:123], v[170:171], off
	global_load_dwordx4 v[124:127], v[172:173], off
	global_load_dwordx4 v[192:195], v[174:175], off
	v_or_b32_e32 v112, 64, v166
	v_ashrrev_i32_e32 v113, 31, v112
	v_lshlrev_b64 v[206:207], 11, v[112:113]
	v_lshl_add_u64 v[112:113], s[12:13], 0, v[218:219]
	v_lshl_add_u64 v[112:113], v[112:113], 0, v[164:165]
	v_lshl_add_u64 v[114:115], s[8:9], 0, v[206:207]
	v_lshl_add_u64 v[112:113], v[112:113], 0, v[128:129]
	v_lshl_add_u64 v[208:209], v[114:115], 0, v[176:177]
	s_waitcnt vmcnt(0)
; #define GAS __attribute__((address_space(1)))
; DI unsigned pk2(float a, float b) { f32x2 v = {a, b}; bf16x2_t r = __builtin_convertvector(v, bf16x2_t); return __builtin_bit_cast(unsigned, r); }
; DI float bflo(unsigned u) { return __uint_as_float(u << 16); }
; DI float bfhi(unsigned u) { return __uint_as_float(u & 0xffff0000u); }
; DI void store_bf16_row32(bf16_t* rowp, const float (&v)[16], int hh) {
; #pragma unroll
;     for (int p = 0; p < 2; ++p) {
;         unsigned ax = pk2(v[8 * p + 0], v[8 * p + 1]), ay = pk2(v[8 * p + 2], v[8 * p + 3]);
;         unsigned bx = pk2(v[8 * p + 4], v[8 * p + 5]), by = pk2(v[8 * p + 6], v[8 * p + 7]);
;         const auto rx = __builtin_amdgcn_permlane32_swap(ax, bx, false, false);
;         const auto ry = __builtin_amdgcn_permlane32_swap(ay, by, false, false);
;         u32x4 w; w.x = rx[0]; w.y = ry[0]; w.z = rx[1]; w.w = ry[1];
;         *(GAS u32x4*)(rowp + 16 * p + 8 * hh) = w;
;     }
; }
;     DI void operator()(int fbase, int tbase, const f32x16& acc, int r, int hh) const {
;         const int t = tbase + r;
;         const bf16_t* res = xb + (size_t)t * D; const float* gate = mods_l + (t >> 13) * 3072 + 2048;
;         float o[16];
; #pragma unroll
;         for (int g = 0; g < 4; ++g) {
;             const int f = fbase + 8 * g + 4 * hh;
;             const u32x2 rb = *(const GAS u32x2*)(res + f); const f32x4 gg = *(const GAS f32x4*)(gate + f);
;             o[4 * g] = bflo(rb.x) + gg.x * acc[4 * g]; o[4 * g + 1] = bfhi(rb.x) + gg.y * acc[4 * g + 1]; o[4 * g + 2] = bflo(rb.y) + gg.z * acc[4 * g + 2]; o[4 * g + 3] = bfhi(rb.y) + gg.w * acc[4 * g + 3];
;         }
;         store_bf16_row32(x2b + (size_t)t * D + fbase, o, hh);
;     }
	global_load_dwordx2 v[230:231], v[208:209], off
	global_load_dwordx2 v[232:233], v[208:209], off offset:16
	global_load_dwordx2 v[234:235], v[208:209], off offset:32
	global_load_dwordx2 v[236:237], v[208:209], off offset:48
	v_lshlrev_b32_e32 v210, 16, v238
	v_and_b32_e32 v211, 0xffff0000, v238
	v_lshlrev_b32_e32 v196, 16, v239
	v_and_b32_e32 v197, 0xffff0000, v239
	v_lshlrev_b32_e32 v212, 16, v240
	v_and_b32_e32 v213, 0xffff0000, v240
	v_lshlrev_b32_e32 v198, 16, v241
	v_and_b32_e32 v199, 0xffff0000, v241
	v_lshlrev_b32_e32 v214, 16, v242
	v_and_b32_e32 v215, 0xffff0000, v242
	v_lshlrev_b32_e32 v200, 16, v243
	v_and_b32_e32 v201, 0xffff0000, v243
	v_lshlrev_b32_e32 v216, 16, v244
	v_and_b32_e32 v217, 0xffff0000, v244
	v_lshlrev_b32_e32 v204, 16, v245
	v_and_b32_e32 v205, 0xffff0000, v245
	v_pk_fma_f32 v[96:97], v[96:97], v[116:117], v[210:211]
	v_pk_fma_f32 v[98:99], v[98:99], v[118:119], v[196:197]
	v_pk_fma_f32 v[100:101], v[100:101], v[120:121], v[212:213]
	v_pk_fma_f32 v[102:103], v[102:103], v[122:123], v[198:199]
	v_pk_fma_f32 v[104:105], v[104:105], v[124:125], v[214:215]
	v_pk_fma_f32 v[106:107], v[106:107], v[126:127], v[200:201]
	v_pk_fma_f32 v[108:109], v[108:109], v[192:193], v[216:217]
	v_pk_fma_f32 v[110:111], v[110:111], v[194:195], v[204:205]
	v_cvt_pk_bf16_f32 v96, v96, v97
	v_cvt_pk_bf16_f32 v97, v98, v99
	v_cvt_pk_bf16_f32 v98, v100, v101
	v_cvt_pk_bf16_f32 v99, v102, v103
	v_cvt_pk_bf16_f32 v100, v104, v105
	v_cvt_pk_bf16_f32 v101, v106, v107
	v_cvt_pk_bf16_f32 v102, v108, v109
	v_cvt_pk_bf16_f32 v103, v110, v111
	v_permlane32_swap_b32_e32 v96, v98
	v_permlane32_swap_b32_e32 v97, v99
	v_permlane32_swap_b32_e32 v100, v102
	v_permlane32_swap_b32_e32 v101, v103
	global_store_dwordx4 v[112:113], v[96:99], off
	global_store_dwordx4 v[112:113], v[100:103], off offset:32
	s_nop 0
	global_load_dwordx4 v[100:103], v[168:169], off
	global_load_dwordx4 v[104:107], v[170:171], off
	global_load_dwordx4 v[108:111], v[172:173], off
	global_load_dwordx4 v[116:119], v[174:175], off
	v_or_b32_e32 v96, 0x60, v166
	v_ashrrev_i32_e32 v97, 31, v96
	v_lshlrev_b64 v[166:167], 11, v[96:97]
	v_lshl_add_u64 v[96:97], s[12:13], 0, v[206:207]
	v_lshl_add_u64 v[96:97], v[96:97], 0, v[164:165]
	v_lshl_add_u64 v[98:99], s[8:9], 0, v[166:167]
	v_lshl_add_u64 v[96:97], v[96:97], 0, v[128:129]
	v_lshl_add_u64 v[176:177], v[98:99], 0, v[176:177]
	s_waitcnt vmcnt(0)
	global_load_dwordx2 v[238:239], v[176:177], off
	global_load_dwordx2 v[240:241], v[176:177], off offset:16
	global_load_dwordx2 v[242:243], v[176:177], off offset:32
	global_load_dwordx2 v[244:245], v[176:177], off offset:48
	v_lshlrev_b32_e32 v192, 16, v230
	v_and_b32_e32 v193, 0xffff0000, v230
	v_lshlrev_b32_e32 v120, 16, v231
	v_and_b32_e32 v121, 0xffff0000, v231
	v_lshlrev_b32_e32 v194, 16, v232
	v_and_b32_e32 v195, 0xffff0000, v232
	v_lshlrev_b32_e32 v122, 16, v233
	v_and_b32_e32 v123, 0xffff0000, v233
	v_lshlrev_b32_e32 v196, 16, v234
	v_and_b32_e32 v197, 0xffff0000, v234
	v_lshlrev_b32_e32 v124, 16, v235
	v_and_b32_e32 v125, 0xffff0000, v235
	v_lshlrev_b32_e32 v198, 16, v236
	v_and_b32_e32 v199, 0xffff0000, v236
	v_lshlrev_b32_e32 v126, 16, v237
	v_and_b32_e32 v127, 0xffff0000, v237
	v_pk_fma_f32 v[80:81], v[80:81], v[100:101], v[192:193]
	v_pk_fma_f32 v[82:83], v[82:83], v[102:103], v[120:121]
	v_pk_fma_f32 v[84:85], v[84:85], v[104:105], v[194:195]
	v_pk_fma_f32 v[86:87], v[86:87], v[106:107], v[122:123]
	v_pk_fma_f32 v[88:89], v[88:89], v[108:109], v[196:197]
	v_pk_fma_f32 v[90:91], v[90:91], v[110:111], v[124:125]
	v_pk_fma_f32 v[92:93], v[92:93], v[116:117], v[198:199]
	v_pk_fma_f32 v[94:95], v[94:95], v[118:119], v[126:127]
	v_cvt_pk_bf16_f32 v80, v80, v81
	v_cvt_pk_bf16_f32 v81, v82, v83
	v_cvt_pk_bf16_f32 v82, v84, v85
	v_cvt_pk_bf16_f32 v83, v86, v87
	v_cvt_pk_bf16_f32 v84, v88, v89
	v_cvt_pk_bf16_f32 v85, v90, v91
	v_cvt_pk_bf16_f32 v86, v92, v93
	v_cvt_pk_bf16_f32 v87, v94, v95
	v_permlane32_swap_b32_e32 v80, v82
	v_permlane32_swap_b32_e32 v81, v83
	v_permlane32_swap_b32_e32 v84, v86
	v_permlane32_swap_b32_e32 v85, v87
	global_store_dwordx4 v[96:97], v[80:83], off
	global_store_dwordx4 v[96:97], v[84:87], off offset:32
	s_nop 0
	global_load_dwordx4 v[84:87], v[168:169], off
	global_load_dwordx4 v[88:91], v[170:171], off
	global_load_dwordx4 v[92:95], v[172:173], off
	global_load_dwordx4 v[100:103], v[174:175], off
	v_lshl_add_u64 v[80:81], v[154:155], 0, v[146:147]
	v_lshlrev_b64 v[82:83], 1, v[80:81]
	v_lshl_add_u64 v[80:81], s[12:13], 0, v[166:167]
	v_lshl_add_u64 v[80:81], v[80:81], 0, v[164:165]
	v_lshl_add_u64 v[80:81], v[80:81], 0, v[128:129]
	v_lshl_add_u64 v[116:117], v[162:163], 0, v[82:83]
	s_waitcnt vmcnt(0)
; #define GAS __attribute__((address_space(1)))
; DI unsigned pk2(float a, float b) { f32x2 v = {a, b}; bf16x2_t r = __builtin_convertvector(v, bf16x2_t); return __builtin_bit_cast(unsigned, r); }
; DI float bflo(unsigned u) { return __uint_as_float(u << 16); }
; DI float bfhi(unsigned u) { return __uint_as_float(u & 0xffff0000u); }
; DI void store_bf16_row32(bf16_t* rowp, const float (&v)[16], int hh) {
; #pragma unroll
;     for (int p = 0; p < 2; ++p) {
;         unsigned ax = pk2(v[8 * p + 0], v[8 * p + 1]), ay = pk2(v[8 * p + 2], v[8 * p + 3]);
;         unsigned bx = pk2(v[8 * p + 4], v[8 * p + 5]), by = pk2(v[8 * p + 6], v[8 * p + 7]);
;         const auto rx = __builtin_amdgcn_permlane32_swap(ax, bx, false, false);
;         const auto ry = __builtin_amdgcn_permlane32_swap(ay, by, false, false);
;         u32x4 w; w.x = rx[0]; w.y = ry[0]; w.z = rx[1]; w.w = ry[1];
;         *(GAS u32x4*)(rowp + 16 * p + 8 * hh) = w;
;     }
; }
;     DI void operator()(int fbase, int tbase, const f32x16& acc, int r, int hh) const {
;         const int t = tbase + r;
;         const bf16_t* res = xb + (size_t)t * D; const float* gate = mods_l + (t >> 13) * 3072 + 2048;
;         float o[16];
; #pragma unroll
;         for (int g = 0; g < 4; ++g) {
;             const int f = fbase + 8 * g + 4 * hh;
;             const u32x2 rb = *(const GAS u32x2*)(res + f); const f32x4 gg = *(const GAS f32x4*)(gate + f);
;             o[4 * g] = bflo(rb.x) + gg.x * acc[4 * g]; o[4 * g + 1] = bfhi(rb.x) + gg.y * acc[4 * g + 1]; o[4 * g + 2] = bflo(rb.y) + gg.z * acc[4 * g + 2]; o[4 * g + 3] = bfhi(rb.y) + gg.w * acc[4 * g + 3];
;         }
;         store_bf16_row32(x2b + (size_t)t * D + fbase, o, hh);
;     }
	global_load_dwordx2 v[230:231], v[116:117], off offset:64
	global_load_dwordx2 v[232:233], v[116:117], off offset:80
	global_load_dwordx2 v[234:235], v[116:117], off offset:96
	global_load_dwordx2 v[236:237], v[116:117], off offset:112
	v_lshlrev_b32_e32 v118, 16, v238
	v_and_b32_e32 v119, 0xffff0000, v238
	v_lshlrev_b32_e32 v104, 16, v239
	v_and_b32_e32 v105, 0xffff0000, v239
	v_lshlrev_b32_e32 v120, 16, v240
	v_and_b32_e32 v121, 0xffff0000, v240
	v_lshlrev_b32_e32 v106, 16, v241
	v_and_b32_e32 v107, 0xffff0000, v241
	v_lshlrev_b32_e32 v122, 16, v242
	v_and_b32_e32 v123, 0xffff0000, v242
	v_lshlrev_b32_e32 v108, 16, v243
	v_and_b32_e32 v109, 0xffff0000, v243
	v_lshlrev_b32_e32 v124, 16, v244
	v_and_b32_e32 v125, 0xffff0000, v244
	v_lshlrev_b32_e32 v110, 16, v245
	v_and_b32_e32 v111, 0xffff0000, v245
	v_pk_fma_f32 v[64:65], v[64:65], v[84:85], v[118:119]
	v_pk_fma_f32 v[66:67], v[66:67], v[86:87], v[104:105]
	v_pk_fma_f32 v[68:69], v[68:69], v[88:89], v[120:121]
	v_pk_fma_f32 v[70:71], v[70:71], v[90:91], v[106:107]
	v_pk_fma_f32 v[72:73], v[72:73], v[92:93], v[122:123]
	v_pk_fma_f32 v[74:75], v[74:75], v[94:95], v[108:109]
	v_pk_fma_f32 v[76:77], v[76:77], v[100:101], v[124:125]
	v_pk_fma_f32 v[78:79], v[78:79], v[102:103], v[110:111]
	v_cvt_pk_bf16_f32 v64, v64, v65
	v_cvt_pk_bf16_f32 v65, v66, v67
	v_cvt_pk_bf16_f32 v66, v68, v69
	v_cvt_pk_bf16_f32 v67, v70, v71
	v_cvt_pk_bf16_f32 v68, v72, v73
	v_cvt_pk_bf16_f32 v69, v74, v75
	v_cvt_pk_bf16_f32 v70, v76, v77
	v_cvt_pk_bf16_f32 v71, v78, v79
	v_permlane32_swap_b32_e32 v64, v66
	v_permlane32_swap_b32_e32 v65, v67
	v_permlane32_swap_b32_e32 v68, v70
	v_permlane32_swap_b32_e32 v69, v71
	global_store_dwordx4 v[80:81], v[64:67], off
	s_nop 0
	global_store_dwordx4 v[80:81], v[68:71], off offset:32
	v_or_b32_e32 v64, v154, v191
	v_or_b32_e32 v66, 8, v64
	v_ashrrev_i32_e32 v65, 31, v64
	v_or_b32_e32 v68, 16, v64
	v_or_b32_e32 v70, 24, v64
	v_ashrrev_i32_e32 v67, 31, v66
	v_ashrrev_i32_e32 v69, 31, v68
	v_ashrrev_i32_e32 v71, 31, v70
	v_lshl_add_u64 v[64:65], v[64:65], 2, v[158:159]
	v_lshl_add_u64 v[66:67], v[66:67], 2, v[158:159]
	global_load_dwordx4 v[72:75], v[64:65], off
	global_load_dwordx4 v[76:79], v[66:67], off
	v_lshl_add_u64 v[68:69], v[68:69], 2, v[158:159]
	v_lshl_add_u64 v[70:71], v[70:71], 2, v[158:159]
	global_load_dwordx4 v[84:87], v[68:69], off
	global_load_dwordx4 v[88:91], v[70:71], off
	v_lshl_add_u64 v[104:105], v[160:161], 0, v[82:83]
	s_waitcnt vmcnt(0)
	global_load_dwordx2 v[238:239], v[104:105], off offset:64
	global_load_dwordx2 v[240:241], v[104:105], off offset:80
	global_load_dwordx2 v[242:243], v[104:105], off offset:96
	global_load_dwordx2 v[244:245], v[104:105], off offset:112
	v_lshlrev_b32_e32 v106, 16, v230
	v_and_b32_e32 v107, 0xffff0000, v230
	v_lshlrev_b32_e32 v92, 16, v231
	v_and_b32_e32 v93, 0xffff0000, v231
	v_lshlrev_b32_e32 v108, 16, v232
	v_and_b32_e32 v109, 0xffff0000, v232
	v_lshlrev_b32_e32 v94, 16, v233
	v_and_b32_e32 v95, 0xffff0000, v233
	v_lshlrev_b32_e32 v110, 16, v234
	v_and_b32_e32 v111, 0xffff0000, v234
	v_lshlrev_b32_e32 v100, 16, v235
	v_and_b32_e32 v101, 0xffff0000, v235
	v_lshlrev_b32_e32 v116, 16, v236
	v_and_b32_e32 v117, 0xffff0000, v236
	v_lshlrev_b32_e32 v102, 16, v237
	v_and_b32_e32 v103, 0xffff0000, v237
	v_pk_fma_f32 v[48:49], v[48:49], v[72:73], v[106:107]
	v_pk_fma_f32 v[50:51], v[50:51], v[74:75], v[92:93]
	v_pk_fma_f32 v[52:53], v[52:53], v[76:77], v[108:109]
	v_pk_fma_f32 v[54:55], v[54:55], v[78:79], v[94:95]
	v_pk_fma_f32 v[56:57], v[56:57], v[84:85], v[110:111]
	v_pk_fma_f32 v[58:59], v[58:59], v[86:87], v[100:101]
	v_pk_fma_f32 v[60:61], v[60:61], v[88:89], v[116:117]
	v_pk_fma_f32 v[62:63], v[62:63], v[90:91], v[102:103]
	v_cvt_pk_bf16_f32 v48, v48, v49
	v_cvt_pk_bf16_f32 v49, v50, v51
	v_cvt_pk_bf16_f32 v50, v52, v53
	v_cvt_pk_bf16_f32 v51, v54, v55
	v_cvt_pk_bf16_f32 v52, v56, v57
	v_cvt_pk_bf16_f32 v53, v58, v59
	v_cvt_pk_bf16_f32 v54, v60, v61
	v_cvt_pk_bf16_f32 v55, v62, v63
	v_permlane32_swap_b32_e32 v48, v50
	v_permlane32_swap_b32_e32 v49, v51
	v_permlane32_swap_b32_e32 v52, v54
	v_permlane32_swap_b32_e32 v53, v55
	global_store_dwordx4 v[156:157], v[48:51], off offset:64
	global_store_dwordx4 v[156:157], v[52:55], off offset:96
	global_load_dwordx4 v[48:51], v[64:65], off
	global_load_dwordx4 v[52:55], v[66:67], off
	global_load_dwordx4 v[56:59], v[68:69], off
	global_load_dwordx4 v[60:63], v[70:71], off
	v_lshl_add_u64 v[84:85], v[114:115], 0, v[82:83]
	s_waitcnt vmcnt(0)
; #define GAS __attribute__((address_space(1)))
; DI unsigned pk2(float a, float b) { f32x2 v = {a, b}; bf16x2_t r = __builtin_convertvector(v, bf16x2_t); return __builtin_bit_cast(unsigned, r); }
; DI float bflo(unsigned u) { return __uint_as_float(u << 16); }
; DI float bfhi(unsigned u) { return __uint_as_float(u & 0xffff0000u); }
; DI void store_bf16_row32(bf16_t* rowp, const float (&v)[16], int hh) {
; #pragma unroll
;     for (int p = 0; p < 2; ++p) {
;         unsigned ax = pk2(v[8 * p + 0], v[8 * p + 1]), ay = pk2(v[8 * p + 2], v[8 * p + 3]);
;         unsigned bx = pk2(v[8 * p + 4], v[8 * p + 5]), by = pk2(v[8 * p + 6], v[8 * p + 7]);
;         const auto rx = __builtin_amdgcn_permlane32_swap(ax, bx, false, false);
;         const auto ry = __builtin_amdgcn_permlane32_swap(ay, by, false, false);
;         u32x4 w; w.x = rx[0]; w.y = ry[0]; w.z = rx[1]; w.w = ry[1];
;         *(GAS u32x4*)(rowp + 16 * p + 8 * hh) = w;
;     }
; }
;     DI void operator()(int fbase, int tbase, const f32x16& acc, int r, int hh) const {
;         const int t = tbase + r;
;         const bf16_t* res = xb + (size_t)t * D; const float* gate = mods_l + (t >> 13) * 3072 + 2048;
;         float o[16];
; #pragma unroll
;         for (int g = 0; g < 4; ++g) {
;             const int f = fbase + 8 * g + 4 * hh;
;             const u32x2 rb = *(const GAS u32x2*)(res + f); const f32x4 gg = *(const GAS f32x4*)(gate + f);
;             o[4 * g] = bflo(rb.x) + gg.x * acc[4 * g]; o[4 * g + 1] = bfhi(rb.x) + gg.y * acc[4 * g + 1]; o[4 * g + 2] = bflo(rb.y) + gg.z * acc[4 * g + 2]; o[4 * g + 3] = bfhi(rb.y) + gg.w * acc[4 * g + 3];
;         }
;         store_bf16_row32(x2b + (size_t)t * D + fbase, o, hh);
;     }
	global_load_dwordx2 v[230:231], v[84:85], off offset:64
	global_load_dwordx2 v[232:233], v[84:85], off offset:80
	global_load_dwordx2 v[234:235], v[84:85], off offset:96
	global_load_dwordx2 v[236:237], v[84:85], off offset:112
	v_lshlrev_b32_e32 v86, 16, v238
	v_and_b32_e32 v87, 0xffff0000, v238
	v_lshlrev_b32_e32 v72, 16, v239
	v_and_b32_e32 v73, 0xffff0000, v239
	v_lshlrev_b32_e32 v88, 16, v240
	v_and_b32_e32 v89, 0xffff0000, v240
	v_lshlrev_b32_e32 v74, 16, v241
	v_and_b32_e32 v75, 0xffff0000, v241
	v_lshlrev_b32_e32 v90, 16, v242
	v_and_b32_e32 v91, 0xffff0000, v242
	v_lshlrev_b32_e32 v76, 16, v243
	v_and_b32_e32 v77, 0xffff0000, v243
	v_lshlrev_b32_e32 v92, 16, v244
	v_and_b32_e32 v93, 0xffff0000, v244
	v_lshlrev_b32_e32 v78, 16, v245
	v_and_b32_e32 v79, 0xffff0000, v245
	v_pk_fma_f32 v[32:33], v[32:33], v[48:49], v[86:87]
	v_pk_fma_f32 v[34:35], v[34:35], v[50:51], v[72:73]
	v_pk_fma_f32 v[36:37], v[36:37], v[52:53], v[88:89]
	v_pk_fma_f32 v[38:39], v[38:39], v[54:55], v[74:75]
	v_pk_fma_f32 v[40:41], v[40:41], v[56:57], v[90:91]
	v_pk_fma_f32 v[42:43], v[42:43], v[58:59], v[76:77]
	v_pk_fma_f32 v[44:45], v[44:45], v[60:61], v[92:93]
	v_pk_fma_f32 v[46:47], v[46:47], v[62:63], v[78:79]
	v_cvt_pk_bf16_f32 v32, v32, v33
	v_cvt_pk_bf16_f32 v33, v34, v35
	v_cvt_pk_bf16_f32 v34, v36, v37
	v_cvt_pk_bf16_f32 v35, v38, v39
	v_cvt_pk_bf16_f32 v36, v40, v41
	v_cvt_pk_bf16_f32 v37, v42, v43
	v_cvt_pk_bf16_f32 v38, v44, v45
	v_cvt_pk_bf16_f32 v39, v46, v47
	v_permlane32_swap_b32_e32 v32, v34
	v_permlane32_swap_b32_e32 v33, v35
	v_permlane32_swap_b32_e32 v36, v38
	v_permlane32_swap_b32_e32 v37, v39
	global_store_dwordx4 v[112:113], v[32:35], off offset:64
	global_store_dwordx4 v[112:113], v[36:39], off offset:96
	global_load_dwordx4 v[32:35], v[64:65], off
	global_load_dwordx4 v[36:39], v[66:67], off
	global_load_dwordx4 v[40:43], v[68:69], off
	global_load_dwordx4 v[44:47], v[70:71], off
	v_lshl_add_u64 v[56:57], v[98:99], 0, v[82:83]
	s_waitcnt vmcnt(0)
	global_load_dwordx2 v[238:239], v[56:57], off offset:64
	global_load_dwordx2 v[240:241], v[56:57], off offset:80
	global_load_dwordx2 v[242:243], v[56:57], off offset:96
	global_load_dwordx2 v[244:245], v[56:57], off offset:112
	v_lshlrev_b32_e32 v58, 16, v230
	v_and_b32_e32 v59, 0xffff0000, v230
	v_lshlrev_b32_e32 v48, 16, v231
	v_and_b32_e32 v49, 0xffff0000, v231
	v_lshlrev_b32_e32 v60, 16, v232
	v_and_b32_e32 v61, 0xffff0000, v232
	v_lshlrev_b32_e32 v50, 16, v233
	v_and_b32_e32 v51, 0xffff0000, v233
	v_lshlrev_b32_e32 v62, 16, v234
	v_and_b32_e32 v63, 0xffff0000, v234
	v_lshlrev_b32_e32 v52, 16, v235
	v_and_b32_e32 v53, 0xffff0000, v235
	v_lshlrev_b32_e32 v72, 16, v236
	v_and_b32_e32 v73, 0xffff0000, v236
	v_lshlrev_b32_e32 v54, 16, v237
	v_and_b32_e32 v55, 0xffff0000, v237
	v_pk_fma_f32 v[16:17], v[16:17], v[32:33], v[58:59]
	v_pk_fma_f32 v[18:19], v[18:19], v[34:35], v[48:49]
	v_pk_fma_f32 v[20:21], v[20:21], v[36:37], v[60:61]
	v_pk_fma_f32 v[22:23], v[22:23], v[38:39], v[50:51]
	v_pk_fma_f32 v[24:25], v[24:25], v[40:41], v[62:63]
	v_pk_fma_f32 v[26:27], v[26:27], v[42:43], v[52:53]
	v_pk_fma_f32 v[28:29], v[28:29], v[44:45], v[72:73]
	v_pk_fma_f32 v[30:31], v[30:31], v[46:47], v[54:55]
	v_cvt_pk_bf16_f32 v16, v16, v17
	v_cvt_pk_bf16_f32 v17, v18, v19
	v_cvt_pk_bf16_f32 v18, v20, v21
	v_cvt_pk_bf16_f32 v19, v22, v23
	v_cvt_pk_bf16_f32 v20, v24, v25
	v_cvt_pk_bf16_f32 v21, v26, v27
	v_cvt_pk_bf16_f32 v22, v28, v29
	v_cvt_pk_bf16_f32 v23, v30, v31
	v_permlane32_swap_b32_e32 v16, v18
	v_permlane32_swap_b32_e32 v17, v19
	v_permlane32_swap_b32_e32 v20, v22
	v_permlane32_swap_b32_e32 v21, v23
	global_store_dwordx4 v[96:97], v[16:19], off offset:64
	global_store_dwordx4 v[96:97], v[20:23], off offset:96
	global_load_dwordx4 v[16:19], v[64:65], off
	global_load_dwordx4 v[20:23], v[66:67], off
	global_load_dwordx4 v[24:27], v[68:69], off
	global_load_dwordx4 v[28:31], v[70:71], off
	s_waitcnt vmcnt(0)
	v_lshlrev_b32_e32 v40, 16, v238
	v_and_b32_e32 v41, 0xffff0000, v238
	v_lshlrev_b32_e32 v32, 16, v239
	v_and_b32_e32 v33, 0xffff0000, v239
	v_lshlrev_b32_e32 v42, 16, v240
	v_and_b32_e32 v43, 0xffff0000, v240
	v_lshlrev_b32_e32 v34, 16, v241
	v_and_b32_e32 v35, 0xffff0000, v241
	v_lshlrev_b32_e32 v44, 16, v242
	v_and_b32_e32 v45, 0xffff0000, v242
	v_lshlrev_b32_e32 v36, 16, v243
	v_and_b32_e32 v37, 0xffff0000, v243
	v_lshlrev_b32_e32 v46, 16, v244
	v_and_b32_e32 v47, 0xffff0000, v244
	v_lshlrev_b32_e32 v38, 16, v245
	v_and_b32_e32 v39, 0xffff0000, v245
	v_pk_fma_f32 v[0:1], v[0:1], v[16:17], v[40:41]
	v_pk_fma_f32 v[2:3], v[2:3], v[18:19], v[32:33]
	v_pk_fma_f32 v[4:5], v[4:5], v[20:21], v[42:43]
	v_pk_fma_f32 v[6:7], v[6:7], v[22:23], v[34:35]
	v_pk_fma_f32 v[8:9], v[8:9], v[24:25], v[44:45]
	v_pk_fma_f32 v[10:11], v[10:11], v[26:27], v[36:37]
	v_pk_fma_f32 v[12:13], v[12:13], v[28:29], v[46:47]
	v_pk_fma_f32 v[14:15], v[14:15], v[30:31], v[38:39]
	v_cvt_pk_bf16_f32 v0, v0, v1
	v_cvt_pk_bf16_f32 v1, v2, v3
	v_cvt_pk_bf16_f32 v2, v4, v5
	v_cvt_pk_bf16_f32 v3, v6, v7
	v_cvt_pk_bf16_f32 v4, v8, v9
	v_cvt_pk_bf16_f32 v5, v10, v11
	v_cvt_pk_bf16_f32 v6, v12, v13
	v_cvt_pk_bf16_f32 v7, v14, v15
	v_permlane32_swap_b32_e32 v0, v2
	v_permlane32_swap_b32_e32 v1, v3
	v_permlane32_swap_b32_e32 v4, v6
	v_permlane32_swap_b32_e32 v5, v7
	global_store_dwordx4 v[80:81], v[0:3], off offset:64
	global_store_dwordx4 v[80:81], v[4:7], off offset:96
	s_cbranch_vccz .LBB0_1168

; #define GAS __attribute__((address_space(1)))
; DI float bflo(unsigned u) { return __uint_as_float(u << 16); }
; DI float bfhi(unsigned u) { return __uint_as_float(u & 0xffff0000u); }
; DI void final_norm_phase(const float* g, const bf16_t* x2b, float* out, int tid) {
;     ...
;     for (int row0 = gw; row0 < MLAT; row0 += 2 * ngw) {
;         f32x4 v[2][4]; bool ok[2]; int row[2];
; #pragma unroll
;         for (int q = 0; q < 2; ++q) {
;             row[q] = row0 + q * ngw; ok[q] = row[q] < MLAT;
;             const bf16_t* src = x2b + (size_t)(ok[q] ? row[q] : row0) * D;
; #pragma unroll
;             for (int j = 0; j < 4; ++j) { const u32x2 b2 = *(const GAS u32x2*)(src + lane * 4 + 256 * j); v[q][j] = (f32x4){bflo(b2.x), bfhi(b2.x), bflo(b2.y), bfhi(b2.y)}; }
;         }
; #pragma unroll
;         for (int q = 0; q < 2; ++q) {
;             float ss = 0.f;
; #pragma unroll
;             for (int j = 0; j < 4; ++j) ss += (v[q][j].x * v[q][j].x + v[q][j].y * v[q][j].y) + (v[q][j].z * v[q][j].z + v[q][j].w * v[q][j].w);
;             const float rstd = 1.f / sqrtf(wave_sum(ss) * (1.f / D) + EPS);
.LBB0_1238:
	v_ashrrev_i32_e32 v9, 31, v8
	v_lshlrev_b64 v[6:7], 11, v[8:9]
	v_lshl_add_u64 v[6:7], v[0:1], 0, v[6:7]
	global_load_dwordx2 v[14:15], v[6:7], off offset:1536
	global_load_dwordx2 v[16:17], v[6:7], off
	global_load_dwordx2 v[18:19], v[6:7], off offset:512
	global_load_dwordx2 v[20:21], v[6:7], off offset:1024
	global_load_dwordx4 v[10:13], v[2:3], off
	v_add_u32_e32 v64, s16, v8
	v_cmp_gt_i32_e64 s[6:7], s1, v64
	s_nop 1
	v_cndmask_b32_e64 v66, v8, v64, s[6:7]
	v_ashrrev_i32_e32 v67, 31, v66
	v_lshlrev_b64 v[68:69], 11, v[66:67]
	v_lshl_add_u64 v[70:71], v[0:1], 0, v[68:69]
	global_load_dwordx2 v[72:73], v[70:71], off
	v_add_u32_e32 v74, s16, v8
	v_cmp_gt_i32_e64 s[6:7], s1, v74
	s_nop 1
	v_cndmask_b32_e64 v76, v8, v74, s[6:7]
	v_ashrrev_i32_e32 v77, 31, v76
	v_lshlrev_b64 v[78:79], 11, v[76:77]
	v_lshl_add_u64 v[80:81], v[0:1], 0, v[78:79]
	global_load_dwordx2 v[82:83], v[80:81], off offset:512
	v_add_u32_e32 v84, s16, v8
	v_cmp_gt_i32_e64 s[6:7], s1, v84
	s_nop 1
	v_cndmask_b32_e64 v86, v8, v84, s[6:7]
	v_ashrrev_i32_e32 v87, 31, v86
	v_lshlrev_b64 v[88:89], 11, v[86:87]
	v_lshl_add_u64 v[90:91], v[0:1], 0, v[88:89]
	global_load_dwordx2 v[92:93], v[90:91], off offset:1024
	v_add_u32_e32 v94, s16, v8
	v_cmp_gt_i32_e64 s[6:7], s1, v94
	s_nop 1
	v_cndmask_b32_e64 v96, v8, v94, s[6:7]
	v_ashrrev_i32_e32 v97, 31, v96
	v_lshlrev_b64 v[98:99], 11, v[96:97]
	v_lshl_add_u64 v[100:101], v[0:1], 0, v[98:99]
	global_load_dwordx2 v[102:103], v[100:101], off offset:1536
	global_load_dwordx4 v[104:107], v[2:3], off offset:1024
	global_load_dwordx4 v[108:111], v[2:3], off offset:2048
	global_load_dwordx4 v[112:115], v[2:3], off offset:3072
	s_waitcnt vmcnt(11)
	v_lshlrev_b32_e32 v7, 16, v14
	v_and_b32_e32 v47, 0xffff0000, v14
	v_lshlrev_b32_e32 v48, 16, v15
	v_and_b32_e32 v49, 0xffff0000, v15
	s_waitcnt vmcnt(10)
	v_lshlrev_b32_e32 v14, 16, v16
	v_and_b32_e32 v15, 0xffff0000, v16
	v_lshlrev_b32_e32 v16, 16, v17
	v_and_b32_e32 v17, 0xffff0000, v17
	s_waitcnt vmcnt(9)
	v_lshlrev_b32_e32 v23, 16, v19
	v_lshlrev_b32_e32 v22, 16, v18
	v_and_b32_e32 v19, 0xffff0000, v19
	v_and_b32_e32 v18, 0xffff0000, v18
	s_waitcnt vmcnt(8)
	v_and_b32_e32 v43, 0xffff0000, v20
	v_mul_f32_e32 v6, v17, v17
	v_mul_f32_e32 v46, v15, v15
	v_lshlrev_b32_e32 v42, 16, v20
	v_lshlrev_b32_e32 v20, 16, v21
	v_and_b32_e32 v21, 0xffff0000, v21
	v_pk_mul_f32 v[44:45], v[18:19], v[18:19]
	v_mov_b32_e32 v51, v7
	v_mul_f32_e32 v50, v43, v43
	v_pk_fma_f32 v[54:55], v[16:17], v[16:17], v[6:7] op_sel_hi:[1,1,0]
	v_pk_fma_f32 v[56:57], v[14:15], v[14:15], v[46:47] op_sel_hi:[1,1,0]
	v_mul_f32_e32 v52, v21, v21
	v_pk_fma_f32 v[44:45], v[22:23], v[22:23], v[44:45]
	v_pk_fma_f32 v[58:59], v[42:43], v[42:43], v[50:51] op_sel_hi:[1,1,0]
	v_mov_b32_e32 v6, v56
	v_mov_b32_e32 v50, v54
	s_waitcnt lgkmcnt(0)
	v_mul_f32_e32 v41, v47, v47
	v_mul_f32_e32 v60, v48, v48
	v_mul_f32_e32 v61, v49, v49
	v_pk_fma_f32 v[52:53], v[20:21], v[20:21], v[52:53] op_sel_hi:[1,1,0]
	v_pk_add_f32 v[54:55], v[56:57], v[54:55]
	v_pk_add_f32 v[44:45], v[44:45], v[44:45] op_sel:[0,1] op_sel_hi:[1,0]
	v_pk_mul_f32 v[50:51], v[6:7], v[50:51]
	v_mov_b32_e32 v59, v60
	v_mov_b32_e32 v53, v61
	v_mov_b32_e32 v45, v41
	v_mov_b32_e32 v55, v51
	v_pk_add_f32 v[52:53], v[58:59], v[52:53]
	v_pk_add_f32 v[44:45], v[54:55], v[44:45]
	s_nop 0
	v_pk_add_f32 v[44:45], v[44:45], v[52:53]
	s_nop 0
	v_add_f32_e32 v6, v44, v45
	ds_bpermute_b32 v41, v35, v6
	s_waitcnt lgkmcnt(0)
	v_add_f32_e32 v6, v6, v41
	ds_bpermute_b32 v41, v36, v6
	s_waitcnt lgkmcnt(0)
	v_add_f32_e32 v6, v6, v41
	ds_bpermute_b32 v41, v37, v6
	s_waitcnt lgkmcnt(0)
	v_add_f32_e32 v6, v6, v41
	ds_bpermute_b32 v41, v38, v6
	s_waitcnt lgkmcnt(0)
	v_add_f32_e32 v41, v6, v41
	ds_bpermute_b32 v44, v39, v41
	v_add_u32_e32 v6, s16, v8
	v_cmp_gt_i32_e64 s[6:7], s1, v6
	s_waitcnt lgkmcnt(0)
	v_add_f32_e32 v41, v41, v44
	ds_bpermute_b32 v46, v40, v41
	v_cndmask_b32_e64 v44, v8, v6, s[6:7]
	v_lshlrev_b64 v[8:9], 12, v[8:9]
	v_ashrrev_i32_e32 v45, 31, v44
	v_lshl_add_u64 v[50:51], v[4:5], 0, v[8:9]
	s_waitcnt lgkmcnt(0)
	v_add_f32_e32 v41, v41, v46
	v_fmamk_f32 v41, v41, 0x3a800000, v25
	v_mul_f32_e32 v46, 0x4f800000, v41
	v_cmp_gt_f32_e32 vcc, s18, v41
	v_lshlrev_b64 v[8:9], 11, v[44:45]
	v_lshl_add_u64 v[8:9], v[0:1], 0, v[8:9]
	v_cndmask_b32_e32 v41, v41, v46, vcc
	v_sqrt_f32_e32 v46, v41
	s_nop 0
	v_add_u32_e32 v44, -1, v46
	v_add_u32_e32 v45, 1, v46
	v_fma_f32 v52, -v44, v46, v41
	v_fma_f32 v53, -v45, v46, v41
	v_cmp_ge_f32_e64 s[2:3], 0, v52
	s_nop 1
	v_cndmask_b32_e64 v44, v46, v44, s[2:3]
	v_cmp_lt_f32_e64 s[2:3], 0, v53
	s_nop 1
	v_cndmask_b32_e64 v44, v44, v45, s[2:3]
	v_mul_f32_e32 v45, 0x37800000, v44
	v_cndmask_b32_e32 v44, v44, v45, vcc
	v_cmp_class_f32_e32 vcc, v41, v26
	s_nop 1
	v_cndmask_b32_e32 v41, v44, v41, vcc
	v_div_scale_f32 v44, s[2:3], v41, v41, 1.0
	v_rcp_f32_e32 v45, v44
	v_div_scale_f32 v8, vcc, 1.0, v41, 1.0
	v_fma_f32 v9, -v44, v45, 1.0
	v_fmac_f32_e32 v45, v9, v45
	v_mul_f32_e32 v9, v8, v45
	v_fma_f32 v46, -v44, v9, v8
	v_fmac_f32_e32 v9, v46, v45
	v_fma_f32 v8, -v44, v9, v8
	v_div_fmas_f32 v8, v8, v45, v9
	v_div_fixup_f32 v60, v8, v41, 1.0
	v_pk_mul_f32 v[8:9], v[60:61], v[14:15] op_sel_hi:[0,1]
	v_pk_mul_f32 v[14:15], v[60:61], v[16:17] op_sel_hi:[0,1]
	s_waitcnt vmcnt(7)
; #define GAS __attribute__((address_space(1)))
; DI void final_norm_phase(const float* g, const bf16_t* x2b, float* out, int tid) {
;     ...
; #pragma unroll
;         for (int q = 0; q < 2; ++q) {
;             float ss = 0.f;
; #pragma unroll
;             for (int j = 0; j < 4; ++j) ss += (v[q][j].x * v[q][j].x + v[q][j].y * v[q][j].y) + (v[q][j].z * v[q][j].z + v[q][j].w * v[q][j].w);
;             const float rstd = 1.f / sqrtf(wave_sum(ss) * (1.f / D) + EPS);
;             if (ok[q]) {
; #pragma unroll
;                 for (int j = 0; j < 4; ++j) { const f32x4 gg = *(const GAS f32x4*)(g + lane * 4 + 256 * j); *(GAS f32x4*)(out + (size_t)row[q] * D + lane * 4 + 256 * j) = v[q][j] * rstd * gg; }
;             }
	v_pk_mul_f32 v[12:13], v[12:13], v[14:15]
	v_pk_mul_f32 v[10:11], v[10:11], v[8:9]
	global_store_dwordx4 v[50:51], v[10:13], off
	s_nop 0
	v_pk_mul_f32 v[48:49], v[60:61], v[48:49] op_sel_hi:[0,1]
	v_mov_b32_e32 v12, v23
	v_mov_b32_e32 v13, v19
	v_mov_b32_e32 v23, v18
	v_pk_mul_f32 v[12:13], v[60:61], v[12:13] op_sel_hi:[0,1]
	v_pk_mul_f32 v[14:15], v[60:61], v[22:23] op_sel_hi:[0,1]
	s_waitcnt vmcnt(7)
	v_and_b32_e32 v23, 0xffff0000, v72
	s_waitcnt vmcnt(6)
	v_and_b32_e32 v17, 0xffff0000, v82
	v_and_b32_e32 v19, 0xffff0000, v83
	v_lshlrev_b32_e32 v22, 16, v72
	v_lshlrev_b32_e32 v16, 16, v82
	v_lshlrev_b32_e32 v18, 16, v83
	v_mul_f32_e32 v41, v23, v23
	v_mul_f32_e32 v52, v17, v17
	v_fmac_f32_e32 v41, v22, v22
	v_fmac_f32_e32 v52, v16, v16
	s_waitcnt vmcnt(3)
	v_pk_mul_f32 v[8:9], v[104:105], v[14:15]
	v_pk_mul_f32 v[10:11], v[106:107], v[12:13]
	global_store_dwordx4 v[50:51], v[8:11], off offset:1024
	v_pk_mul_f32 v[12:13], v[60:61], v[20:21] op_sel_hi:[0,1]
	v_pk_mul_f32 v[14:15], v[60:61], v[42:43] op_sel_hi:[0,1]
	v_and_b32_e32 v21, 0xffff0000, v73
	v_lshlrev_b32_e32 v20, 16, v73
	v_mul_f32_e32 v46, v21, v21
	v_mul_f32_e32 v53, v19, v19
	v_fmac_f32_e32 v46, v20, v20
	v_fmac_f32_e32 v53, v18, v18
	v_add_f32_e32 v41, v41, v46
	v_add_f32_e32 v46, v52, v53
	v_add_f32_e32 v41, v41, v46
	s_waitcnt vmcnt(3)
	v_pk_mul_f32 v[8:9], v[108:109], v[14:15]
	v_pk_mul_f32 v[10:11], v[110:111], v[12:13]
	global_store_dwordx4 v[50:51], v[8:11], off offset:2048
	v_and_b32_e32 v13, 0xffff0000, v92
	v_and_b32_e32 v15, 0xffff0000, v93
	v_lshlrev_b32_e32 v12, 16, v92
	v_lshlrev_b32_e32 v14, 16, v93
	v_and_b32_e32 v9, 0xffff0000, v102
	v_and_b32_e32 v11, 0xffff0000, v103
	v_mul_f32_e32 v54, v13, v13
	v_mul_f32_e32 v55, v15, v15
	v_lshlrev_b32_e32 v8, 16, v102
	v_lshlrev_b32_e32 v10, 16, v103
	v_mul_f32_e32 v56, v9, v9
	v_mul_f32_e32 v57, v11, v11
	v_fmac_f32_e32 v54, v12, v12
	v_fmac_f32_e32 v55, v14, v14
	v_fmac_f32_e32 v56, v8, v8
	v_fmac_f32_e32 v57, v10, v10
	v_add_f32_e32 v52, v54, v55
	v_add_f32_e32 v53, v56, v57
	v_add_f32_e32 v41, v41, v52
	v_add_f32_e32 v41, v41, v53
	ds_bpermute_b32 v46, v35, v41
	s_waitcnt lgkmcnt(0)
	v_add_f32_e32 v41, v41, v46
	ds_bpermute_b32 v46, v36, v41
	s_waitcnt lgkmcnt(0)
	v_add_f32_e32 v41, v41, v46
	ds_bpermute_b32 v46, v37, v41
	s_waitcnt lgkmcnt(0)
	v_add_f32_e32 v41, v41, v46
	ds_bpermute_b32 v46, v38, v41
	s_waitcnt lgkmcnt(0)
	v_add_f32_e32 v41, v41, v46
	ds_bpermute_b32 v52, v39, v41
	v_mov_b32_e32 v46, v7
	v_pk_mul_f32 v[46:47], v[60:61], v[46:47] op_sel_hi:[0,1]
	s_waitcnt lgkmcnt(0)
	v_add_f32_e32 v7, v41, v52
	ds_bpermute_b32 v41, v40, v7
	s_waitcnt vmcnt(3)
	v_pk_mul_f32 v[42:43], v[112:113], v[46:47]
	v_pk_mul_f32 v[44:45], v[114:115], v[48:49]
	global_store_dwordx4 v[50:51], v[42:45], off offset:3072
	s_and_saveexec_b64 s[14:15], s[6:7]
	s_cbranch_execz .LBB0_1237
	global_load_dwordx4 v[42:45], v[2:3], off
	global_load_dwordx4 v[116:119], v[2:3], off offset:1024
	global_load_dwordx4 v[120:123], v[2:3], off offset:2048
	global_load_dwordx4 v[124:127], v[2:3], off offset:3072
	s_waitcnt lgkmcnt(0)
	v_add_f32_e32 v7, v7, v41
	v_fmamk_f32 v7, v7, 0x3a800000, v25
	v_mul_f32_e32 v41, 0x4f800000, v7
	v_cmp_gt_f32_e32 vcc, s18, v7
	s_nop 1
	v_cndmask_b32_e32 v41, v7, v41, vcc
	v_sqrt_f32_e32 v48, v41
	v_ashrrev_i32_e32 v7, 31, v6
	v_lshlrev_b64 v[46:47], 12, v[6:7]
	v_lshl_add_u64 v[46:47], v[4:5], 0, v[46:47]
	v_add_u32_e32 v7, -1, v48
	v_add_u32_e32 v49, 1, v48
	v_fma_f32 v50, -v7, v48, v41
	v_fma_f32 v51, -v49, v48, v41
	v_cmp_ge_f32_e64 s[2:3], 0, v50
	s_nop 1
	v_cndmask_b32_e64 v7, v48, v7, s[2:3]
	v_cmp_lt_f32_e64 s[2:3], 0, v51
	s_nop 1
	v_cndmask_b32_e64 v7, v7, v49, s[2:3]
	v_mul_f32_e32 v48, 0x37800000, v7
	v_cndmask_b32_e32 v7, v7, v48, vcc
	v_cmp_class_f32_e32 vcc, v41, v26
	s_nop 1
	v_cndmask_b32_e32 v7, v7, v41, vcc
	v_div_scale_f32 v41, s[2:3], v7, v7, 1.0
	v_rcp_f32_e32 v48, v41
	v_div_scale_f32 v49, vcc, 1.0, v7, 1.0
	v_fma_f32 v50, -v41, v48, 1.0
	v_fmac_f32_e32 v48, v50, v48
	v_mul_f32_e32 v50, v49, v48
	v_fma_f32 v51, -v41, v50, v49
	v_fmac_f32_e32 v50, v51, v48
	v_fma_f32 v41, -v41, v50, v49
	v_div_fmas_f32 v41, v41, v48, v50
	v_div_fixup_f32 v48, v41, v7, 1.0
	v_pk_mul_f32 v[50:51], v[48:49], v[22:23] op_sel_hi:[0,1]
	v_pk_mul_f32 v[20:21], v[48:49], v[20:21] op_sel_hi:[0,1]
	v_pk_mul_f32 v[18:19], v[48:49], v[18:19] op_sel_hi:[0,1]
	v_pk_mul_f32 v[16:17], v[48:49], v[16:17] op_sel_hi:[0,1]
	v_pk_mul_f32 v[14:15], v[48:49], v[14:15] op_sel_hi:[0,1]
	v_pk_mul_f32 v[12:13], v[48:49], v[12:13] op_sel_hi:[0,1]
	v_pk_mul_f32 v[10:11], v[48:49], v[10:11] op_sel_hi:[0,1]
	v_pk_mul_f32 v[8:9], v[48:49], v[8:9] op_sel_hi:[0,1]
	s_waitcnt vmcnt(3)
	v_pk_mul_f32 v[22:23], v[20:21], v[44:45]
	v_pk_mul_f32 v[20:21], v[50:51], v[42:43]
	global_store_dwordx4 v[46:47], v[20:23], off
	s_waitcnt vmcnt(3)
	v_pk_mul_f32 v[16:17], v[16:17], v[116:117]
	v_pk_mul_f32 v[18:19], v[18:19], v[118:119]
	global_store_dwordx4 v[46:47], v[16:19], off offset:1024
	s_waitcnt vmcnt(3)
	v_pk_mul_f32 v[12:13], v[12:13], v[120:121]
	v_pk_mul_f32 v[14:15], v[14:15], v[122:123]
	global_store_dwordx4 v[46:47], v[12:15], off offset:2048
	s_waitcnt vmcnt(3)
	v_pk_mul_f32 v[8:9], v[8:9], v[124:125]
	v_pk_mul_f32 v[10:11], v[10:11], v[126:127]
	global_store_dwordx4 v[46:47], v[8:11], off offset:3072
	s_branch .LBB0_1237
